# lever 7 instruction selection: gate epilogue bias-add + scale folded into v_pk_fma_f32 (bias pre-scaled once per tile), 64 VALU fewer per gate tile
# speedup vs baseline: 1.0069x; 1.0018x over previous
; #define GAS __attribute__((address_space(1)))
; __device__ __forceinline__ float sigmoidf_(float x) { return frcp(1.f + fexp2(-x * LOG2E)); }
; __device__ __forceinline__ float siluf_(float x) { return x * sigmoidf_(x); }
; __device__ __forceinline__ u32x4 pack8(f32x4 a, f32x4 b) { u32x4 w; w.x = pk2(a[0], a[1]); w.y = pk2(a[2], a[3]); w.z = pk2(b[0], b[1]); w.w = pk2(b[2], b[3]); return w; }
;     __device__ __forceinline__ void operator()(const f32x4 (&acc)[2][2][4][2], const Unit& u, int wr, int wc, int fr, int fq) const {
; #pragma unroll
;         for (int ai = 0; ai < 2; ++ai)
; #pragma unroll
;             for (int m = 0; m < 4; ++m) {
;                 const int row = u.pm * BM + ai * HALF + wr * 64 + m * 16 + fr;
; #pragma unroll
;                 for (int bj = 0; bj < 2; ++bj) f(u, row, bj * HALF + wc * 32 + 8 * fq, acc[ai][bj][m][0], acc[ai][bj][m][1]);
;             }
;     __device__ __forceinline__ void operator()(const Unit& u, int row, int col, f32x4 v0, f32x4 v1) const {
;     ...
;             const int pc = pn * 256 - 512 + col;
;             if (pn >= 10) {
;                 const f32x4 b0 = *(const GAS f32x4*)(b_gate + pc - PC_GATE), b1 = *(const GAS f32x4*)(b_gate + pc - PC_GATE + 4);
; #pragma unroll
;                 for (int i = 0; i < 4; ++i) { v0[i] = sigmoidf_(v0[i] + b0[i]); v1[i] = sigmoidf_(v1[i] + b1[i]); }
;             } else if (pn == 8 || pn == 9) {
;                 const float sc = 0.08838834764831845f * LOG2E;
;                 v0 = v0 * sc; v1 = v1 * sc;
;             } else {
; #pragma unroll
;                 for (int i = 0; i < 4; ++i) { v0[i] = siluf_(v0[i]); v1[i] = siluf_(v1[i]); }
;             }
;             __builtin_nontemporal_store(pack8(v0, v1), (GAS u32x4*)(P + (size_t)row * PW + pc));
.Lfp_cls3:
	s_mov_b32 s98, 0xbfb8aa3b
	s_mov_b32 s100, 1.0
	s_lshl_b32 s57, s6, 8
	s_add_i32 s57, s57, s85
	s_lshl_b32 s68, s76, 8
	s_add_i32 s38, s68, 0xffffea00
	v_or_b32_e32 v150, s57, v162
	s_and_b32 s8, s76, 14
	v_ashrrev_i32_e32 v151, 31, v150
	v_lshlrev_b64 v[152:153], 10, v[150:151]
	v_mad_i64_i32 v[150:151], s[8:9], v150, s10, 0
	s_ashr_i32 s69, s68, 31
	v_lshl_add_u64 v[196:197], s[68:69], 0, v[136:137]
	v_lshl_add_u64 v[204:205], s[68:69], 0, v[138:139]
	s_waitcnt lgkmcnt(0)
	v_lshl_add_u64 v[196:197], v[196:197], 2, s[36:37]
	v_lshl_add_u64 v[204:205], v[204:205], 2, s[36:37]
	v_lshl_add_u64 v[200:201], v[196:197], 0, s[54:55]
	v_lshl_add_u64 v[208:209], v[204:205], 0, s[54:55]
	v_add_co_u32_e32 v196, vcc, 0xffffe000, v196
	s_nop 1
	v_addc_co_u32_e32 v197, vcc, -1, v197, vcc
	v_add_co_u32_e32 v204, vcc, 0xffffe000, v204
	s_nop 1
	v_addc_co_u32_e32 v205, vcc, -1, v205, vcc
	global_load_dwordx4 v[196:199], v[196:197], off offset:-2048
	global_load_dwordx4 v[200:203], v[200:201], off offset:16
	global_load_dwordx4 v[204:207], v[204:205], off offset:-2048
	global_load_dwordx4 v[208:211], v[208:209], off offset:16
	s_waitcnt vmcnt(2)
	v_pk_mul_f32 v[196:197], v[196:197], s[98:99] op_sel_hi:[1,0]
	v_pk_mul_f32 v[198:199], v[198:199], s[98:99] op_sel_hi:[1,0]
	v_pk_mul_f32 v[200:201], v[200:201], s[98:99] op_sel_hi:[1,0]
	v_pk_mul_f32 v[202:203], v[202:203], s[98:99] op_sel_hi:[1,0]
	v_pk_fma_f32 v[212:213], v[120:121], s[98:99], v[196:197] op_sel_hi:[1,0,1]
	v_pk_fma_f32 v[214:215], v[122:123], s[98:99], v[198:199] op_sel_hi:[1,0,1]
	v_pk_fma_f32 v[216:217], v[124:125], s[98:99], v[200:201] op_sel_hi:[1,0,1]
	v_pk_fma_f32 v[218:219], v[126:127], s[98:99], v[202:203] op_sel_hi:[1,0,1]
	v_exp_f32_e32 v212, v212
	v_exp_f32_e32 v213, v213
	v_exp_f32_e32 v214, v214
	v_exp_f32_e32 v215, v215
	v_exp_f32_e32 v216, v216
	v_exp_f32_e32 v217, v217
	v_exp_f32_e32 v218, v218
	v_exp_f32_e32 v219, v219
	v_pk_add_f32 v[212:213], v[212:213], s[100:101] op_sel_hi:[1,0]
	v_pk_add_f32 v[214:215], v[214:215], s[100:101] op_sel_hi:[1,0]
	v_pk_add_f32 v[216:217], v[216:217], s[100:101] op_sel_hi:[1,0]
	v_pk_add_f32 v[218:219], v[218:219], s[100:101] op_sel_hi:[1,0]
	v_rcp_f32_e32 v156, v212
	v_rcp_f32_e32 v157, v213
	v_rcp_f32_e32 v154, v214
	v_rcp_f32_e32 v155, v215
	v_rcp_f32_e32 v160, v216
	v_rcp_f32_e32 v161, v217
	v_rcp_f32_e32 v158, v218
	v_rcp_f32_e32 v159, v219
	s_ashr_i32 s69, s68, 31
	v_cvt_pk_bf16_f32 v170, v156, v157
	v_cvt_pk_bf16_f32 v171, v154, v155
	v_lshl_add_u64 v[154:155], s[42:43], 0, v[150:151]
	v_lshl_add_u64 v[156:157], s[68:69], 0, v[136:137]
	v_cvt_pk_bf16_f32 v172, v160, v161
	v_cvt_pk_bf16_f32 v173, v158, v159
	v_lshl_add_u64 v[154:155], v[156:157], 1, v[154:155]
	global_store_dwordx4 v[154:155], v[170:173], off offset:-1024 nt
	s_lshl_b32 s21, s76, 15
	v_add_u32_e32 v154, s21, v164
	s_ashr_i32 s59, s57, 4
	v_and_b32_e32 v154, 0xfffff800, v154
	s_nop 1
	s_waitcnt vmcnt(1)
	v_pk_mul_f32 v[204:205], v[204:205], s[98:99] op_sel_hi:[1,0]
	v_pk_mul_f32 v[206:207], v[206:207], s[98:99] op_sel_hi:[1,0]
	v_pk_mul_f32 v[208:209], v[208:209], s[98:99] op_sel_hi:[1,0]
	v_pk_mul_f32 v[210:211], v[210:211], s[98:99] op_sel_hi:[1,0]
	v_pk_fma_f32 v[212:213], v[112:113], s[98:99], v[208:209] op_sel_hi:[1,0,1]
	v_pk_fma_f32 v[214:215], v[114:115], s[98:99], v[210:211] op_sel_hi:[1,0,1]
	v_pk_fma_f32 v[216:217], v[116:117], s[98:99], v[204:205] op_sel_hi:[1,0,1]
	v_pk_fma_f32 v[218:219], v[118:119], s[98:99], v[206:207] op_sel_hi:[1,0,1]
	v_exp_f32_e32 v212, v212
	v_exp_f32_e32 v213, v213
	v_exp_f32_e32 v214, v214
	v_exp_f32_e32 v215, v215
	v_exp_f32_e32 v216, v216
	v_exp_f32_e32 v217, v217
	v_exp_f32_e32 v218, v218
	v_exp_f32_e32 v219, v219
	v_pk_add_f32 v[212:213], v[212:213], s[100:101] op_sel_hi:[1,0]
	v_pk_add_f32 v[214:215], v[214:215], s[100:101] op_sel_hi:[1,0]
	v_pk_add_f32 v[216:217], v[216:217], s[100:101] op_sel_hi:[1,0]
	v_pk_add_f32 v[218:219], v[218:219], s[100:101] op_sel_hi:[1,0]
	v_rcp_f32_e32 v126, v212
	v_rcp_f32_e32 v127, v213
	v_rcp_f32_e32 v124, v214
	v_rcp_f32_e32 v125, v215
	v_rcp_f32_e32 v122, v216
	v_rcp_f32_e32 v123, v217
	v_rcp_f32_e32 v120, v218
	v_rcp_f32_e32 v121, v219
	s_ashr_i32 s69, s68, 31
	v_cvt_pk_bf16_f32 v156, v122, v123
	v_cvt_pk_bf16_f32 v157, v120, v121
	v_lshl_add_u64 v[120:121], s[42:43], 0, v[150:151]
	v_lshl_add_u64 v[122:123], s[68:69], 0, v[138:139]
	v_cvt_pk_bf16_f32 v158, v126, v127
	v_cvt_pk_bf16_f32 v159, v124, v125
	v_lshl_add_u64 v[120:121], v[122:123], 1, v[120:121]
	global_store_dwordx4 v[120:121], v[156:159], off offset:-1024 nt
	v_add_u32_e32 v120, s21, v165
	v_and_b32_e32 v124, 0xfffff800, v120
	s_or_b32 s21, s57, 16
	v_or_b32_e32 v112, s21, v162
	v_ashrrev_i32_e32 v113, 31, v112
	v_lshlrev_b64 v[114:115], 10, v[112:113]
	v_mad_i64_i32 v[112:113], s[74:75], v112, s10, 0
	v_pk_fma_f32 v[212:213], v[104:105], s[98:99], v[200:201] op_sel_hi:[1,0,1]
	v_pk_fma_f32 v[214:215], v[106:107], s[98:99], v[202:203] op_sel_hi:[1,0,1]
	v_pk_fma_f32 v[216:217], v[108:109], s[98:99], v[196:197] op_sel_hi:[1,0,1]
	v_pk_fma_f32 v[218:219], v[110:111], s[98:99], v[198:199] op_sel_hi:[1,0,1]
	v_exp_f32_e32 v212, v212
	v_exp_f32_e32 v213, v213
	v_exp_f32_e32 v214, v214
	v_exp_f32_e32 v215, v215
	v_exp_f32_e32 v216, v216
	v_exp_f32_e32 v217, v217
	v_exp_f32_e32 v218, v218
	v_exp_f32_e32 v219, v219
	v_pk_add_f32 v[212:213], v[212:213], s[100:101] op_sel_hi:[1,0]
	v_pk_add_f32 v[214:215], v[214:215], s[100:101] op_sel_hi:[1,0]
	v_pk_add_f32 v[216:217], v[216:217], s[100:101] op_sel_hi:[1,0]
	v_pk_add_f32 v[218:219], v[218:219], s[100:101] op_sel_hi:[1,0]
	v_rcp_f32_e32 v122, v212
	v_rcp_f32_e32 v123, v213
; #define GAS __attribute__((address_space(1)))
; __device__ __forceinline__ float sigmoidf_(float x) { return frcp(1.f + fexp2(-x * LOG2E)); }
; __device__ __forceinline__ float siluf_(float x) { return x * sigmoidf_(x); }
; __device__ __forceinline__ u32x4 pack8(f32x4 a, f32x4 b) { u32x4 w; w.x = pk2(a[0], a[1]); w.y = pk2(a[2], a[3]); w.z = pk2(b[0], b[1]); w.w = pk2(b[2], b[3]); return w; }
;     __device__ __forceinline__ void operator()(const f32x4 (&acc)[2][2][4][2], const Unit& u, int wr, int wc, int fr, int fq) const {
; #pragma unroll
;         for (int ai = 0; ai < 2; ++ai)
; #pragma unroll
;             for (int m = 0; m < 4; ++m) {
;                 const int row = u.pm * BM + ai * HALF + wr * 64 + m * 16 + fr;
; #pragma unroll
;                 for (int bj = 0; bj < 2; ++bj) f(u, row, bj * HALF + wc * 32 + 8 * fq, acc[ai][bj][m][0], acc[ai][bj][m][1]);
;             }
;     __device__ __forceinline__ void operator()(const Unit& u, int row, int col, f32x4 v0, f32x4 v1) const {
;     ...
;             const int pc = pn * 256 - 512 + col;
;             if (pn >= 10) {
;                 const f32x4 b0 = *(const GAS f32x4*)(b_gate + pc - PC_GATE), b1 = *(const GAS f32x4*)(b_gate + pc - PC_GATE + 4);
; #pragma unroll
;                 for (int i = 0; i < 4; ++i) { v0[i] = sigmoidf_(v0[i] + b0[i]); v1[i] = sigmoidf_(v1[i] + b1[i]); }
;             } else if (pn == 8 || pn == 9) {
;                 const float sc = 0.08838834764831845f * LOG2E;
;                 v0 = v0 * sc; v1 = v1 * sc;
;             } else {
; #pragma unroll
;                 for (int i = 0; i < 4; ++i) { v0[i] = siluf_(v0[i]); v1[i] = siluf_(v1[i]); }
;             }
;             __builtin_nontemporal_store(pack8(v0, v1), (GAS u32x4*)(P + (size_t)row * PW + pc));
	v_rcp_f32_e32 v120, v214
	v_rcp_f32_e32 v121, v215
	v_rcp_f32_e32 v118, v216
	v_rcp_f32_e32 v119, v217
	v_rcp_f32_e32 v116, v218
	v_rcp_f32_e32 v117, v219
	s_ashr_i32 s69, s68, 31
	v_cvt_pk_bf16_f32 v150, v118, v119
	v_cvt_pk_bf16_f32 v151, v116, v117
	v_lshl_add_u64 v[116:117], s[42:43], 0, v[112:113]
	v_lshl_add_u64 v[118:119], s[68:69], 0, v[136:137]
	v_cvt_pk_bf16_f32 v152, v122, v123
	v_cvt_pk_bf16_f32 v153, v120, v121
	v_lshl_add_u64 v[116:117], v[118:119], 1, v[116:117]
	global_store_dwordx4 v[116:117], v[150:153], off offset:-1024 nt
	s_ashr_i32 s21, s21, 4
	v_pk_fma_f32 v[212:213], v[96:97], s[98:99], v[208:209] op_sel_hi:[1,0,1]
	v_pk_fma_f32 v[214:215], v[98:99], s[98:99], v[210:211] op_sel_hi:[1,0,1]
	v_pk_fma_f32 v[216:217], v[100:101], s[98:99], v[204:205] op_sel_hi:[1,0,1]
	v_pk_fma_f32 v[218:219], v[102:103], s[98:99], v[206:207] op_sel_hi:[1,0,1]
	v_exp_f32_e32 v212, v212
	v_exp_f32_e32 v213, v213
	v_exp_f32_e32 v214, v214
	v_exp_f32_e32 v215, v215
	v_exp_f32_e32 v216, v216
	v_exp_f32_e32 v217, v217
	v_exp_f32_e32 v218, v218
	v_exp_f32_e32 v219, v219
	v_pk_add_f32 v[212:213], v[212:213], s[100:101] op_sel_hi:[1,0]
	v_pk_add_f32 v[214:215], v[214:215], s[100:101] op_sel_hi:[1,0]
	v_pk_add_f32 v[216:217], v[216:217], s[100:101] op_sel_hi:[1,0]
	v_pk_add_f32 v[218:219], v[218:219], s[100:101] op_sel_hi:[1,0]
	v_rcp_f32_e32 v110, v212
	v_rcp_f32_e32 v111, v213
	v_rcp_f32_e32 v108, v214
	v_rcp_f32_e32 v109, v215
	v_rcp_f32_e32 v106, v216
	v_rcp_f32_e32 v107, v217
	v_rcp_f32_e32 v104, v218
	v_rcp_f32_e32 v105, v219
	s_ashr_i32 s69, s68, 31
	v_cvt_pk_bf16_f32 v114, v106, v107
	v_cvt_pk_bf16_f32 v115, v104, v105
	v_lshl_add_u64 v[104:105], s[42:43], 0, v[112:113]
	v_lshl_add_u64 v[106:107], s[68:69], 0, v[138:139]
	v_cvt_pk_bf16_f32 v116, v110, v111
	v_cvt_pk_bf16_f32 v117, v108, v109
	v_lshl_add_u64 v[104:105], v[106:107], 1, v[104:105]
	global_store_dwordx4 v[104:105], v[114:117], off offset:-1024 nt
	s_or_b32 s21, s57, 32
	v_or_b32_e32 v96, s21, v162
	v_ashrrev_i32_e32 v97, 31, v96
	v_lshlrev_b64 v[98:99], 10, v[96:97]
	v_mad_i64_i32 v[96:97], s[74:75], v96, s10, 0
	v_pk_fma_f32 v[212:213], v[88:89], s[98:99], v[200:201] op_sel_hi:[1,0,1]
	v_pk_fma_f32 v[214:215], v[90:91], s[98:99], v[202:203] op_sel_hi:[1,0,1]
	v_pk_fma_f32 v[216:217], v[92:93], s[98:99], v[196:197] op_sel_hi:[1,0,1]
	v_pk_fma_f32 v[218:219], v[94:95], s[98:99], v[198:199] op_sel_hi:[1,0,1]
	v_exp_f32_e32 v212, v212
	v_exp_f32_e32 v213, v213
	v_exp_f32_e32 v214, v214
	v_exp_f32_e32 v215, v215
	v_exp_f32_e32 v216, v216
	v_exp_f32_e32 v217, v217
	v_exp_f32_e32 v218, v218
	v_exp_f32_e32 v219, v219
	v_pk_add_f32 v[212:213], v[212:213], s[100:101] op_sel_hi:[1,0]
	v_pk_add_f32 v[214:215], v[214:215], s[100:101] op_sel_hi:[1,0]
	v_pk_add_f32 v[216:217], v[216:217], s[100:101] op_sel_hi:[1,0]
	v_pk_add_f32 v[218:219], v[218:219], s[100:101] op_sel_hi:[1,0]
	v_rcp_f32_e32 v106, v212
	v_rcp_f32_e32 v107, v213
	v_rcp_f32_e32 v104, v214
	v_rcp_f32_e32 v105, v215
	v_rcp_f32_e32 v102, v216
	v_rcp_f32_e32 v103, v217
	v_rcp_f32_e32 v100, v218
	v_rcp_f32_e32 v101, v219
	s_ashr_i32 s69, s68, 31
	v_cvt_pk_bf16_f32 v108, v102, v103
	v_cvt_pk_bf16_f32 v109, v100, v101
	v_lshl_add_u64 v[100:101], s[42:43], 0, v[96:97]
	v_lshl_add_u64 v[102:103], s[68:69], 0, v[136:137]
	v_cvt_pk_bf16_f32 v110, v106, v107
	v_cvt_pk_bf16_f32 v111, v104, v105
	v_lshl_add_u64 v[100:101], v[102:103], 1, v[100:101]
	global_store_dwordx4 v[100:101], v[108:111], off offset:-1024 nt
	s_ashr_i32 s21, s21, 4
	v_pk_fma_f32 v[212:213], v[80:81], s[98:99], v[208:209] op_sel_hi:[1,0,1]
	v_pk_fma_f32 v[214:215], v[82:83], s[98:99], v[210:211] op_sel_hi:[1,0,1]
	v_pk_fma_f32 v[216:217], v[84:85], s[98:99], v[204:205] op_sel_hi:[1,0,1]
	v_pk_fma_f32 v[218:219], v[86:87], s[98:99], v[206:207] op_sel_hi:[1,0,1]
	v_exp_f32_e32 v212, v212
	v_exp_f32_e32 v213, v213
	v_exp_f32_e32 v214, v214
	v_exp_f32_e32 v215, v215
	v_exp_f32_e32 v216, v216
	v_exp_f32_e32 v217, v217
	v_exp_f32_e32 v218, v218
	v_exp_f32_e32 v219, v219
	v_pk_add_f32 v[212:213], v[212:213], s[100:101] op_sel_hi:[1,0]
	v_pk_add_f32 v[214:215], v[214:215], s[100:101] op_sel_hi:[1,0]
	v_pk_add_f32 v[216:217], v[216:217], s[100:101] op_sel_hi:[1,0]
	v_pk_add_f32 v[218:219], v[218:219], s[100:101] op_sel_hi:[1,0]
	v_rcp_f32_e32 v94, v212
	v_rcp_f32_e32 v95, v213
	v_rcp_f32_e32 v92, v214
	v_rcp_f32_e32 v93, v215
	v_rcp_f32_e32 v90, v216
	v_rcp_f32_e32 v91, v217
	v_rcp_f32_e32 v88, v218
	v_rcp_f32_e32 v89, v219
	s_ashr_i32 s69, s68, 31
	v_cvt_pk_bf16_f32 v98, v90, v91
	v_cvt_pk_bf16_f32 v99, v88, v89
	v_lshl_add_u64 v[88:89], s[42:43], 0, v[96:97]
	v_lshl_add_u64 v[90:91], s[68:69], 0, v[138:139]
	v_cvt_pk_bf16_f32 v100, v94, v95
	v_cvt_pk_bf16_f32 v101, v92, v93
	v_lshl_add_u64 v[88:89], v[90:91], 1, v[88:89]
	global_store_dwordx4 v[88:89], v[98:101], off offset:-1024 nt
	s_or_b32 s21, s57, 48
	v_or_b32_e32 v80, s21, v162
	v_ashrrev_i32_e32 v81, 31, v80
	v_lshlrev_b64 v[82:83], 10, v[80:81]
	v_mad_i64_i32 v[80:81], s[74:75], v80, s10, 0
	v_pk_fma_f32 v[212:213], v[72:73], s[98:99], v[200:201] op_sel_hi:[1,0,1]
	v_pk_fma_f32 v[214:215], v[74:75], s[98:99], v[202:203] op_sel_hi:[1,0,1]
	v_pk_fma_f32 v[216:217], v[76:77], s[98:99], v[196:197] op_sel_hi:[1,0,1]
	v_pk_fma_f32 v[218:219], v[78:79], s[98:99], v[198:199] op_sel_hi:[1,0,1]
	v_exp_f32_e32 v212, v212
	v_exp_f32_e32 v213, v213
	v_exp_f32_e32 v214, v214
	v_exp_f32_e32 v215, v215
	v_exp_f32_e32 v216, v216
	v_exp_f32_e32 v217, v217
	v_exp_f32_e32 v218, v218
	v_exp_f32_e32 v219, v219
	v_pk_add_f32 v[212:213], v[212:213], s[100:101] op_sel_hi:[1,0]
	v_pk_add_f32 v[214:215], v[214:215], s[100:101] op_sel_hi:[1,0]
; #define GAS __attribute__((address_space(1)))
; __device__ __forceinline__ float sigmoidf_(float x) { return frcp(1.f + fexp2(-x * LOG2E)); }
; __device__ __forceinline__ float siluf_(float x) { return x * sigmoidf_(x); }
; __device__ __forceinline__ u32x4 pack8(f32x4 a, f32x4 b) { u32x4 w; w.x = pk2(a[0], a[1]); w.y = pk2(a[2], a[3]); w.z = pk2(b[0], b[1]); w.w = pk2(b[2], b[3]); return w; }
;     __device__ __forceinline__ void operator()(const f32x4 (&acc)[2][2][4][2], const Unit& u, int wr, int wc, int fr, int fq) const {
; #pragma unroll
;         for (int ai = 0; ai < 2; ++ai)
; #pragma unroll
;             for (int m = 0; m < 4; ++m) {
;                 const int row = u.pm * BM + ai * HALF + wr * 64 + m * 16 + fr;
; #pragma unroll
;                 for (int bj = 0; bj < 2; ++bj) f(u, row, bj * HALF + wc * 32 + 8 * fq, acc[ai][bj][m][0], acc[ai][bj][m][1]);
;             }
;     __device__ __forceinline__ void operator()(const Unit& u, int row, int col, f32x4 v0, f32x4 v1) const {
;     ...
;             const int pc = pn * 256 - 512 + col;
;             if (pn >= 10) {
;                 const f32x4 b0 = *(const GAS f32x4*)(b_gate + pc - PC_GATE), b1 = *(const GAS f32x4*)(b_gate + pc - PC_GATE + 4);
; #pragma unroll
;                 for (int i = 0; i < 4; ++i) { v0[i] = sigmoidf_(v0[i] + b0[i]); v1[i] = sigmoidf_(v1[i] + b1[i]); }
;             } else if (pn == 8 || pn == 9) {
;                 const float sc = 0.08838834764831845f * LOG2E;
;                 v0 = v0 * sc; v1 = v1 * sc;
;             } else {
; #pragma unroll
;                 for (int i = 0; i < 4; ++i) { v0[i] = siluf_(v0[i]); v1[i] = siluf_(v1[i]); }
;             }
;             __builtin_nontemporal_store(pack8(v0, v1), (GAS u32x4*)(P + (size_t)row * PW + pc));
	v_pk_add_f32 v[216:217], v[216:217], s[100:101] op_sel_hi:[1,0]
	v_pk_add_f32 v[218:219], v[218:219], s[100:101] op_sel_hi:[1,0]
	v_rcp_f32_e32 v90, v212
	v_rcp_f32_e32 v91, v213
	v_rcp_f32_e32 v88, v214
	v_rcp_f32_e32 v89, v215
	v_rcp_f32_e32 v86, v216
	v_rcp_f32_e32 v87, v217
	v_rcp_f32_e32 v84, v218
	v_rcp_f32_e32 v85, v219
	s_ashr_i32 s69, s68, 31
	v_cvt_pk_bf16_f32 v92, v86, v87
	v_cvt_pk_bf16_f32 v93, v84, v85
	v_lshl_add_u64 v[84:85], s[42:43], 0, v[80:81]
	v_lshl_add_u64 v[86:87], s[68:69], 0, v[136:137]
	v_cvt_pk_bf16_f32 v94, v90, v91
	v_cvt_pk_bf16_f32 v95, v88, v89
	v_lshl_add_u64 v[84:85], v[86:87], 1, v[84:85]
	global_store_dwordx4 v[84:85], v[92:95], off offset:-1024 nt
	s_ashr_i32 s21, s21, 4
	v_pk_fma_f32 v[212:213], v[64:65], s[98:99], v[208:209] op_sel_hi:[1,0,1]
	v_pk_fma_f32 v[214:215], v[66:67], s[98:99], v[210:211] op_sel_hi:[1,0,1]
	v_pk_fma_f32 v[216:217], v[68:69], s[98:99], v[204:205] op_sel_hi:[1,0,1]
	v_pk_fma_f32 v[218:219], v[70:71], s[98:99], v[206:207] op_sel_hi:[1,0,1]
	v_exp_f32_e32 v212, v212
	v_exp_f32_e32 v213, v213
	v_exp_f32_e32 v214, v214
	v_exp_f32_e32 v215, v215
	v_exp_f32_e32 v216, v216
	v_exp_f32_e32 v217, v217
	v_exp_f32_e32 v218, v218
	v_exp_f32_e32 v219, v219
	v_pk_add_f32 v[212:213], v[212:213], s[100:101] op_sel_hi:[1,0]
	v_pk_add_f32 v[214:215], v[214:215], s[100:101] op_sel_hi:[1,0]
	v_pk_add_f32 v[216:217], v[216:217], s[100:101] op_sel_hi:[1,0]
	v_pk_add_f32 v[218:219], v[218:219], s[100:101] op_sel_hi:[1,0]
	v_rcp_f32_e32 v78, v212
	v_rcp_f32_e32 v79, v213
	v_rcp_f32_e32 v76, v214
	v_rcp_f32_e32 v77, v215
	v_rcp_f32_e32 v74, v216
	v_rcp_f32_e32 v75, v217
	v_rcp_f32_e32 v72, v218
	v_rcp_f32_e32 v73, v219
	s_ashr_i32 s69, s68, 31
	v_cvt_pk_bf16_f32 v82, v74, v75
	v_cvt_pk_bf16_f32 v83, v72, v73
	v_lshl_add_u64 v[72:73], s[42:43], 0, v[80:81]
	v_lshl_add_u64 v[74:75], s[68:69], 0, v[138:139]
	v_cvt_pk_bf16_f32 v84, v78, v79
	v_cvt_pk_bf16_f32 v85, v76, v77
	v_lshl_add_u64 v[72:73], v[74:75], 1, v[72:73]
	global_store_dwordx4 v[72:73], v[82:85], off offset:-1024 nt
	s_add_i32 s21, s57, 0x80
	v_or_b32_e32 v64, s21, v162
	v_ashrrev_i32_e32 v65, 31, v64
	v_lshlrev_b64 v[66:67], 10, v[64:65]
	v_mad_i64_i32 v[64:65], s[74:75], v64, s10, 0
	v_pk_fma_f32 v[212:213], v[56:57], s[98:99], v[200:201] op_sel_hi:[1,0,1]
	v_pk_fma_f32 v[214:215], v[58:59], s[98:99], v[202:203] op_sel_hi:[1,0,1]
	v_pk_fma_f32 v[216:217], v[60:61], s[98:99], v[196:197] op_sel_hi:[1,0,1]
	v_pk_fma_f32 v[218:219], v[62:63], s[98:99], v[198:199] op_sel_hi:[1,0,1]
	v_exp_f32_e32 v212, v212
	v_exp_f32_e32 v213, v213
	v_exp_f32_e32 v214, v214
	v_exp_f32_e32 v215, v215
	v_exp_f32_e32 v216, v216
	v_exp_f32_e32 v217, v217
	v_exp_f32_e32 v218, v218
	v_exp_f32_e32 v219, v219
	v_pk_add_f32 v[212:213], v[212:213], s[100:101] op_sel_hi:[1,0]
	v_pk_add_f32 v[214:215], v[214:215], s[100:101] op_sel_hi:[1,0]
	v_pk_add_f32 v[216:217], v[216:217], s[100:101] op_sel_hi:[1,0]
	v_pk_add_f32 v[218:219], v[218:219], s[100:101] op_sel_hi:[1,0]
	v_rcp_f32_e32 v74, v212
	v_rcp_f32_e32 v75, v213
	v_rcp_f32_e32 v72, v214
	v_rcp_f32_e32 v73, v215
	v_rcp_f32_e32 v70, v216
	v_rcp_f32_e32 v71, v217
	v_rcp_f32_e32 v68, v218
	v_rcp_f32_e32 v69, v219
	s_ashr_i32 s69, s68, 31
	v_cvt_pk_bf16_f32 v76, v70, v71
	v_cvt_pk_bf16_f32 v77, v68, v69
	v_lshl_add_u64 v[68:69], s[42:43], 0, v[64:65]
	v_lshl_add_u64 v[70:71], s[68:69], 0, v[136:137]
	v_cvt_pk_bf16_f32 v78, v74, v75
	v_cvt_pk_bf16_f32 v79, v72, v73
	v_lshl_add_u64 v[68:69], v[70:71], 1, v[68:69]
	global_store_dwordx4 v[68:69], v[76:79], off offset:-1024 nt
	s_ashr_i32 s21, s21, 4
	v_pk_fma_f32 v[212:213], v[48:49], s[98:99], v[208:209] op_sel_hi:[1,0,1]
	v_pk_fma_f32 v[214:215], v[50:51], s[98:99], v[210:211] op_sel_hi:[1,0,1]
	v_pk_fma_f32 v[216:217], v[52:53], s[98:99], v[204:205] op_sel_hi:[1,0,1]
	v_pk_fma_f32 v[218:219], v[54:55], s[98:99], v[206:207] op_sel_hi:[1,0,1]
	v_exp_f32_e32 v212, v212
	v_exp_f32_e32 v213, v213
	v_exp_f32_e32 v214, v214
	v_exp_f32_e32 v215, v215
	v_exp_f32_e32 v216, v216
	v_exp_f32_e32 v217, v217
	v_exp_f32_e32 v218, v218
	v_exp_f32_e32 v219, v219
	v_pk_add_f32 v[212:213], v[212:213], s[100:101] op_sel_hi:[1,0]
	v_pk_add_f32 v[214:215], v[214:215], s[100:101] op_sel_hi:[1,0]
	v_pk_add_f32 v[216:217], v[216:217], s[100:101] op_sel_hi:[1,0]
	v_pk_add_f32 v[218:219], v[218:219], s[100:101] op_sel_hi:[1,0]
	v_rcp_f32_e32 v62, v212
	v_rcp_f32_e32 v63, v213
	v_rcp_f32_e32 v60, v214
	v_rcp_f32_e32 v61, v215
	v_rcp_f32_e32 v58, v216
	v_rcp_f32_e32 v59, v217
	v_rcp_f32_e32 v56, v218
	v_rcp_f32_e32 v57, v219
	s_ashr_i32 s69, s68, 31
	v_cvt_pk_bf16_f32 v66, v58, v59
	v_cvt_pk_bf16_f32 v67, v56, v57
	v_lshl_add_u64 v[56:57], s[42:43], 0, v[64:65]
	v_lshl_add_u64 v[58:59], s[68:69], 0, v[138:139]
	v_cvt_pk_bf16_f32 v68, v62, v63
	v_cvt_pk_bf16_f32 v69, v60, v61
	v_lshl_add_u64 v[56:57], v[58:59], 1, v[56:57]
	global_store_dwordx4 v[56:57], v[66:69], off offset:-1024 nt
	s_add_i32 s21, s57, 0x90
	v_or_b32_e32 v48, s21, v162
	v_ashrrev_i32_e32 v49, 31, v48
	v_lshlrev_b64 v[50:51], 10, v[48:49]
	v_mad_i64_i32 v[48:49], s[74:75], v48, s10, 0
	v_pk_fma_f32 v[212:213], v[40:41], s[98:99], v[200:201] op_sel_hi:[1,0,1]
	v_pk_fma_f32 v[214:215], v[42:43], s[98:99], v[202:203] op_sel_hi:[1,0,1]
	v_pk_fma_f32 v[216:217], v[44:45], s[98:99], v[196:197] op_sel_hi:[1,0,1]
	v_pk_fma_f32 v[218:219], v[46:47], s[98:99], v[198:199] op_sel_hi:[1,0,1]
	v_exp_f32_e32 v212, v212
	v_exp_f32_e32 v213, v213
	v_exp_f32_e32 v214, v214
	v_exp_f32_e32 v215, v215
	v_exp_f32_e32 v216, v216
	v_exp_f32_e32 v217, v217
	v_exp_f32_e32 v218, v218
	v_exp_f32_e32 v219, v219
	v_pk_add_f32 v[212:213], v[212:213], s[100:101] op_sel_hi:[1,0]
; #define GAS __attribute__((address_space(1)))
; __device__ __forceinline__ float sigmoidf_(float x) { return frcp(1.f + fexp2(-x * LOG2E)); }
; __device__ __forceinline__ float siluf_(float x) { return x * sigmoidf_(x); }
; __device__ __forceinline__ u32x4 pack8(f32x4 a, f32x4 b) { u32x4 w; w.x = pk2(a[0], a[1]); w.y = pk2(a[2], a[3]); w.z = pk2(b[0], b[1]); w.w = pk2(b[2], b[3]); return w; }
;     __device__ __forceinline__ void operator()(const f32x4 (&acc)[2][2][4][2], const Unit& u, int wr, int wc, int fr, int fq) const {
; #pragma unroll
;         for (int ai = 0; ai < 2; ++ai)
; #pragma unroll
;             for (int m = 0; m < 4; ++m) {
;                 const int row = u.pm * BM + ai * HALF + wr * 64 + m * 16 + fr;
; #pragma unroll
;                 for (int bj = 0; bj < 2; ++bj) f(u, row, bj * HALF + wc * 32 + 8 * fq, acc[ai][bj][m][0], acc[ai][bj][m][1]);
;             }
;     __device__ __forceinline__ void operator()(const Unit& u, int row, int col, f32x4 v0, f32x4 v1) const {
;     ...
;             const int pc = pn * 256 - 512 + col;
;             if (pn >= 10) {
;                 const f32x4 b0 = *(const GAS f32x4*)(b_gate + pc - PC_GATE), b1 = *(const GAS f32x4*)(b_gate + pc - PC_GATE + 4);
; #pragma unroll
;                 for (int i = 0; i < 4; ++i) { v0[i] = sigmoidf_(v0[i] + b0[i]); v1[i] = sigmoidf_(v1[i] + b1[i]); }
;             } else if (pn == 8 || pn == 9) {
;                 const float sc = 0.08838834764831845f * LOG2E;
;                 v0 = v0 * sc; v1 = v1 * sc;
;             } else {
; #pragma unroll
;                 for (int i = 0; i < 4; ++i) { v0[i] = siluf_(v0[i]); v1[i] = siluf_(v1[i]); }
;             }
;             __builtin_nontemporal_store(pack8(v0, v1), (GAS u32x4*)(P + (size_t)row * PW + pc));
	v_pk_add_f32 v[214:215], v[214:215], s[100:101] op_sel_hi:[1,0]
	v_pk_add_f32 v[216:217], v[216:217], s[100:101] op_sel_hi:[1,0]
	v_pk_add_f32 v[218:219], v[218:219], s[100:101] op_sel_hi:[1,0]
	v_rcp_f32_e32 v58, v212
	v_rcp_f32_e32 v59, v213
	v_rcp_f32_e32 v56, v214
	v_rcp_f32_e32 v57, v215
	v_rcp_f32_e32 v54, v216
	v_rcp_f32_e32 v55, v217
	v_rcp_f32_e32 v52, v218
	v_rcp_f32_e32 v53, v219
	s_ashr_i32 s69, s68, 31
	v_cvt_pk_bf16_f32 v60, v54, v55
	v_cvt_pk_bf16_f32 v61, v52, v53
	v_lshl_add_u64 v[52:53], s[42:43], 0, v[48:49]
	v_lshl_add_u64 v[54:55], s[68:69], 0, v[136:137]
	v_cvt_pk_bf16_f32 v62, v58, v59
	v_cvt_pk_bf16_f32 v63, v56, v57
	v_lshl_add_u64 v[52:53], v[54:55], 1, v[52:53]
	global_store_dwordx4 v[52:53], v[60:63], off offset:-1024 nt
	s_ashr_i32 s21, s21, 4
	v_pk_fma_f32 v[212:213], v[32:33], s[98:99], v[208:209] op_sel_hi:[1,0,1]
	v_pk_fma_f32 v[214:215], v[34:35], s[98:99], v[210:211] op_sel_hi:[1,0,1]
	v_pk_fma_f32 v[216:217], v[36:37], s[98:99], v[204:205] op_sel_hi:[1,0,1]
	v_pk_fma_f32 v[218:219], v[38:39], s[98:99], v[206:207] op_sel_hi:[1,0,1]
	v_exp_f32_e32 v212, v212
	v_exp_f32_e32 v213, v213
	v_exp_f32_e32 v214, v214
	v_exp_f32_e32 v215, v215
	v_exp_f32_e32 v216, v216
	v_exp_f32_e32 v217, v217
	v_exp_f32_e32 v218, v218
	v_exp_f32_e32 v219, v219
	v_pk_add_f32 v[212:213], v[212:213], s[100:101] op_sel_hi:[1,0]
	v_pk_add_f32 v[214:215], v[214:215], s[100:101] op_sel_hi:[1,0]
	v_pk_add_f32 v[216:217], v[216:217], s[100:101] op_sel_hi:[1,0]
	v_pk_add_f32 v[218:219], v[218:219], s[100:101] op_sel_hi:[1,0]
	v_rcp_f32_e32 v46, v212
	v_rcp_f32_e32 v47, v213
	v_rcp_f32_e32 v44, v214
	v_rcp_f32_e32 v45, v215
	v_rcp_f32_e32 v42, v216
	v_rcp_f32_e32 v43, v217
	v_rcp_f32_e32 v40, v218
	v_rcp_f32_e32 v41, v219
	s_ashr_i32 s69, s68, 31
	v_cvt_pk_bf16_f32 v50, v42, v43
	v_cvt_pk_bf16_f32 v51, v40, v41
	v_lshl_add_u64 v[40:41], s[42:43], 0, v[48:49]
	v_lshl_add_u64 v[42:43], s[68:69], 0, v[138:139]
	v_cvt_pk_bf16_f32 v52, v46, v47
	v_cvt_pk_bf16_f32 v53, v44, v45
	v_lshl_add_u64 v[40:41], v[42:43], 1, v[40:41]
	global_store_dwordx4 v[40:41], v[50:53], off offset:-1024 nt
	s_add_i32 s21, s57, 0xa0
	v_or_b32_e32 v32, s21, v162
	v_ashrrev_i32_e32 v33, 31, v32
	v_lshlrev_b64 v[34:35], 10, v[32:33]
	v_mad_i64_i32 v[32:33], s[74:75], v32, s10, 0
	v_pk_fma_f32 v[212:213], v[24:25], s[98:99], v[200:201] op_sel_hi:[1,0,1]
	v_pk_fma_f32 v[214:215], v[26:27], s[98:99], v[202:203] op_sel_hi:[1,0,1]
	v_pk_fma_f32 v[216:217], v[28:29], s[98:99], v[196:197] op_sel_hi:[1,0,1]
	v_pk_fma_f32 v[218:219], v[30:31], s[98:99], v[198:199] op_sel_hi:[1,0,1]
	v_exp_f32_e32 v212, v212
	v_exp_f32_e32 v213, v213
	v_exp_f32_e32 v214, v214
	v_exp_f32_e32 v215, v215
	v_exp_f32_e32 v216, v216
	v_exp_f32_e32 v217, v217
	v_exp_f32_e32 v218, v218
	v_exp_f32_e32 v219, v219
	v_pk_add_f32 v[212:213], v[212:213], s[100:101] op_sel_hi:[1,0]
	v_pk_add_f32 v[214:215], v[214:215], s[100:101] op_sel_hi:[1,0]
	v_pk_add_f32 v[216:217], v[216:217], s[100:101] op_sel_hi:[1,0]
	v_pk_add_f32 v[218:219], v[218:219], s[100:101] op_sel_hi:[1,0]
	v_rcp_f32_e32 v42, v212
	v_rcp_f32_e32 v43, v213
	v_rcp_f32_e32 v40, v214
	v_rcp_f32_e32 v41, v215
	v_rcp_f32_e32 v38, v216
	v_rcp_f32_e32 v39, v217
	v_rcp_f32_e32 v36, v218
	v_rcp_f32_e32 v37, v219
	s_ashr_i32 s69, s68, 31
	v_cvt_pk_bf16_f32 v44, v38, v39
	v_cvt_pk_bf16_f32 v45, v36, v37
	v_lshl_add_u64 v[36:37], s[42:43], 0, v[32:33]
	v_lshl_add_u64 v[38:39], s[68:69], 0, v[136:137]
	v_cvt_pk_bf16_f32 v46, v42, v43
	v_cvt_pk_bf16_f32 v47, v40, v41
	v_lshl_add_u64 v[36:37], v[38:39], 1, v[36:37]
	global_store_dwordx4 v[36:37], v[44:47], off offset:-1024 nt
	s_ashr_i32 s21, s21, 4
	v_pk_fma_f32 v[212:213], v[16:17], s[98:99], v[208:209] op_sel_hi:[1,0,1]
	v_pk_fma_f32 v[214:215], v[18:19], s[98:99], v[210:211] op_sel_hi:[1,0,1]
	v_pk_fma_f32 v[216:217], v[20:21], s[98:99], v[204:205] op_sel_hi:[1,0,1]
	v_pk_fma_f32 v[218:219], v[22:23], s[98:99], v[206:207] op_sel_hi:[1,0,1]
	v_exp_f32_e32 v212, v212
	v_exp_f32_e32 v213, v213
; #define GAS __attribute__((address_space(1)))
; __device__ __forceinline__ float sigmoidf_(float x) { return frcp(1.f + fexp2(-x * LOG2E)); }
; __device__ __forceinline__ float siluf_(float x) { return x * sigmoidf_(x); }
; #define PG8_BAR __builtin_amdgcn_s_barrier()
; template <class Epi, class Sched>
; __device__ __forceinline__ void gemm_phase(LAS unsigned char* lds, const Gemm g, const Sched& S, const Epi& E, const int wave_) {
;     ...
;         if (wr == 0) PG8_BAR;
;         E(acc, cur, wr, wc, fr, fq);
;         if (!has_next) break;
; #pragma unroll
;         for (int a = 0; a < 2; ++a)
; #pragma unroll
;             for (int b = 0; b < 2; ++b)
; #pragma unroll
;                 for (int m = 0; m < 4; ++m)
; #pragma unroll
;                     for (int n = 0; n < 2; ++n) acc[a][b][m][n] = (f32x4){0.f, 0.f, 0.f, 0.f};
;         cur = nxt; cA = nA; cB = nB; ++ui;
;         if (wr == 1) PG8_BAR;
;     }
;     __device__ __forceinline__ void operator()(const f32x4 (&acc)[2][2][4][2], const Unit& u, int wr, int wc, int fr, int fq) const {
; #pragma unroll
;         for (int ai = 0; ai < 2; ++ai)
; #pragma unroll
;             for (int m = 0; m < 4; ++m) {
;                 const int row = u.pm * BM + ai * HALF + wr * 64 + m * 16 + fr;
; #pragma unroll
;                 for (int bj = 0; bj < 2; ++bj) f(u, row, bj * HALF + wc * 32 + 8 * fq, acc[ai][bj][m][0], acc[ai][bj][m][1]);
;             }
;     __device__ __forceinline__ void operator()(const Unit& u, int row, int col, f32x4 v0, f32x4 v1) const {
;     ...
;             const int pc = pn * 256 - 512 + col;
;             if (pn >= 10) {
;                 const f32x4 b0 = *(const GAS f32x4*)(b_gate + pc - PC_GATE), b1 = *(const GAS f32x4*)(b_gate + pc - PC_GATE + 4);
; #pragma unroll
;                 for (int i = 0; i < 4; ++i) { v0[i] = sigmoidf_(v0[i] + b0[i]); v1[i] = sigmoidf_(v1[i] + b1[i]); }
;             } else if (pn == 8 || pn == 9) {
;                 const float sc = 0.08838834764831845f * LOG2E;
;                 v0 = v0 * sc; v1 = v1 * sc;
;             } else {
; #pragma unroll
;                 for (int i = 0; i < 4; ++i) { v0[i] = siluf_(v0[i]); v1[i] = siluf_(v1[i]); }
;             }
;             __builtin_nontemporal_store(pack8(v0, v1), (GAS u32x4*)(P + (size_t)row * PW + pc));
	v_exp_f32_e32 v214, v214
	v_exp_f32_e32 v215, v215
	v_exp_f32_e32 v216, v216
	v_exp_f32_e32 v217, v217
	v_exp_f32_e32 v218, v218
	v_exp_f32_e32 v219, v219
	v_pk_add_f32 v[212:213], v[212:213], s[100:101] op_sel_hi:[1,0]
	v_pk_add_f32 v[214:215], v[214:215], s[100:101] op_sel_hi:[1,0]
	v_pk_add_f32 v[216:217], v[216:217], s[100:101] op_sel_hi:[1,0]
	v_pk_add_f32 v[218:219], v[218:219], s[100:101] op_sel_hi:[1,0]
	v_rcp_f32_e32 v30, v212
	v_rcp_f32_e32 v31, v213
	v_rcp_f32_e32 v28, v214
	v_rcp_f32_e32 v29, v215
	v_rcp_f32_e32 v26, v216
	v_rcp_f32_e32 v27, v217
	v_rcp_f32_e32 v24, v218
	v_rcp_f32_e32 v25, v219
	s_ashr_i32 s69, s68, 31
	v_cvt_pk_bf16_f32 v34, v26, v27
	v_cvt_pk_bf16_f32 v35, v24, v25
	v_lshl_add_u64 v[24:25], s[42:43], 0, v[32:33]
	v_lshl_add_u64 v[26:27], s[68:69], 0, v[138:139]
	v_cvt_pk_bf16_f32 v36, v30, v31
	v_cvt_pk_bf16_f32 v37, v28, v29
	v_lshl_add_u64 v[24:25], v[26:27], 1, v[24:25]
	global_store_dwordx4 v[24:25], v[34:37], off offset:-1024 nt
	s_addk_i32 s57, 0xb0
	v_or_b32_e32 v16, s57, v162
	v_ashrrev_i32_e32 v17, 31, v16
	v_lshlrev_b64 v[18:19], 10, v[16:17]
	v_mad_i64_i32 v[16:17], s[74:75], v16, s10, 0
	v_pk_fma_f32 v[212:213], v[8:9], s[98:99], v[200:201] op_sel_hi:[1,0,1]
	v_pk_fma_f32 v[214:215], v[10:11], s[98:99], v[202:203] op_sel_hi:[1,0,1]
	v_pk_fma_f32 v[216:217], v[12:13], s[98:99], v[196:197] op_sel_hi:[1,0,1]
	v_pk_fma_f32 v[218:219], v[14:15], s[98:99], v[198:199] op_sel_hi:[1,0,1]
	v_exp_f32_e32 v212, v212
	v_exp_f32_e32 v213, v213
	v_exp_f32_e32 v214, v214
	v_exp_f32_e32 v215, v215
	v_exp_f32_e32 v216, v216
	v_exp_f32_e32 v217, v217
	v_exp_f32_e32 v218, v218
	v_exp_f32_e32 v219, v219
	v_pk_add_f32 v[212:213], v[212:213], s[100:101] op_sel_hi:[1,0]
	v_pk_add_f32 v[214:215], v[214:215], s[100:101] op_sel_hi:[1,0]
	v_pk_add_f32 v[216:217], v[216:217], s[100:101] op_sel_hi:[1,0]
	v_pk_add_f32 v[218:219], v[218:219], s[100:101] op_sel_hi:[1,0]
	v_rcp_f32_e32 v26, v212
	v_rcp_f32_e32 v27, v213
	v_rcp_f32_e32 v24, v214
	v_rcp_f32_e32 v25, v215
	v_rcp_f32_e32 v22, v216
	v_rcp_f32_e32 v23, v217
	v_rcp_f32_e32 v20, v218
	v_rcp_f32_e32 v21, v219
	s_ashr_i32 s69, s68, 31
	v_cvt_pk_bf16_f32 v28, v22, v23
	v_cvt_pk_bf16_f32 v29, v20, v21
	v_lshl_add_u64 v[20:21], s[42:43], 0, v[16:17]
	v_lshl_add_u64 v[22:23], s[68:69], 0, v[136:137]
	v_cvt_pk_bf16_f32 v30, v26, v27
	v_cvt_pk_bf16_f32 v31, v24, v25
	v_lshl_add_u64 v[20:21], v[22:23], 1, v[20:21]
	global_store_dwordx4 v[20:21], v[28:31], off offset:-1024 nt
	s_ashr_i32 s21, s57, 4
	v_pk_fma_f32 v[212:213], v[0:1], s[98:99], v[208:209] op_sel_hi:[1,0,1]
	v_pk_fma_f32 v[214:215], v[2:3], s[98:99], v[210:211] op_sel_hi:[1,0,1]
	v_pk_fma_f32 v[216:217], v[4:5], s[98:99], v[204:205] op_sel_hi:[1,0,1]
	v_pk_fma_f32 v[218:219], v[6:7], s[98:99], v[206:207] op_sel_hi:[1,0,1]
	v_exp_f32_e32 v212, v212
	v_exp_f32_e32 v213, v213
	v_exp_f32_e32 v214, v214
	v_exp_f32_e32 v215, v215
	v_exp_f32_e32 v216, v216
	v_exp_f32_e32 v217, v217
	v_exp_f32_e32 v218, v218
	v_exp_f32_e32 v219, v219
	v_pk_add_f32 v[212:213], v[212:213], s[100:101] op_sel_hi:[1,0]
	v_pk_add_f32 v[214:215], v[214:215], s[100:101] op_sel_hi:[1,0]
	v_pk_add_f32 v[216:217], v[216:217], s[100:101] op_sel_hi:[1,0]
	v_pk_add_f32 v[218:219], v[218:219], s[100:101] op_sel_hi:[1,0]
	v_rcp_f32_e32 v14, v212
	v_rcp_f32_e32 v15, v213
	v_rcp_f32_e32 v12, v214
	v_rcp_f32_e32 v13, v215
	v_rcp_f32_e32 v10, v216
	v_rcp_f32_e32 v11, v217
	v_rcp_f32_e32 v8, v218
	v_rcp_f32_e32 v9, v219
	s_ashr_i32 s69, s68, 31
	v_cvt_pk_bf16_f32 v18, v10, v11
	v_cvt_pk_bf16_f32 v19, v8, v9
	v_lshl_add_u64 v[8:9], s[42:43], 0, v[16:17]
	v_lshl_add_u64 v[10:11], s[68:69], 0, v[138:139]
	v_cvt_pk_bf16_f32 v20, v14, v15
	v_cvt_pk_bf16_f32 v21, v12, v13
	v_lshl_add_u64 v[8:9], v[10:11], 1, v[8:9]
	global_store_dwordx4 v[8:9], v[18:21], off offset:-1024 nt
	s_andn2_b64 vcc, exec, s[4:5]
	s_mov_b64 s[4:5], -1
	s_cbranch_vccnz .LBB0_178
	s_andn2_b64 vcc, exec, s[40:41]
	s_cbranch_vccnz .LBB0_177
	s_barrier
	s_branch .LBB0_177
